# indexer head-weighted relu sum as packed f32 fma chains (even/odd heads) + one add instead of 8 serial f32 adds; still f32
# speedup vs baseline: 1.0096x; 1.0055x over previous
; #define LAS __attribute__((address_space(3)))
; __device__ __forceinline__ void indexer_phase(const bf16_t* PJ, float* rk, unsigned short* SEL, LAS unsigned char* lds) {
;     ...
;                     for (int qq = 0; qq < 2; ++qq) { float s = 0.f;
; #pragma unroll
;                         for (int e = 0; e < 8; ++e) s += wq[rt][qq][e] * fmaxf(acc[8 * qq + e], 0.f);
;                         ((LAS float*)lds)[(4 * rt + 2 * hi + qq) * 4096 + key] = s;
;                         const bool ok = key <= t0 + 4 * rt + 2 * hi + qq;
;                         rmax[rt][qq] = fmaxf(rmax[rt][qq], ok ? s : -INFINITY); rmin[rt][qq] = fminf(rmin[rt][qq], ok ? s : INFINITY); }
.Lidx_trA:
	ds_write_b128 v222, v[52:55]
	ds_write_b128 v222, v[56:59] offset:1024
	s_nop 3
	v_max_f32_e32 v0, 0, v0
	v_max_f32_e32 v1, 0, v1
	v_max_f32_e32 v2, 0, v2
	v_max_f32_e32 v3, 0, v3
	v_max_f32_e32 v4, 0, v4
	v_max_f32_e32 v5, 0, v5
	v_max_f32_e32 v6, 0, v6
	v_max_f32_e32 v7, 0, v7
	v_pk_mul_f32 v[0:1], v[126:127], v[0:1] op_sel:[1,0] op_sel_hi:[0,1]
	v_pk_fma_f32 v[0:1], v[128:129], v[2:3], v[0:1] op_sel:[1,0,0] op_sel_hi:[0,1,1]
	v_pk_fma_f32 v[0:1], v[130:131], v[4:5], v[0:1] op_sel:[1,0,0] op_sel_hi:[0,1,1]
	v_pk_fma_f32 v[0:1], v[132:133], v[6:7], v[0:1] op_sel:[1,0,0] op_sel_hi:[0,1,1]
	v_add_f32_e32 v0, v1, v0
	v_max_f32_e32 v8, 0, v8
	v_max_f32_e32 v9, 0, v9
	v_max_f32_e32 v10, 0, v10
	v_max_f32_e32 v11, 0, v11
	v_max_f32_e32 v12, 0, v12
	v_max_f32_e32 v13, 0, v13
	v_max_f32_e32 v14, 0, v14
	v_max_f32_e32 v15, 0, v15
	s_waitcnt lgkmcnt(0)
	ds_read_b128 v[244:247], v223
	ds_read_b128 v[104:107], v224
	v_pk_mul_f32 v[8:9], v[134:135], v[8:9] op_sel:[1,0] op_sel_hi:[0,1]
	v_pk_fma_f32 v[8:9], v[136:137], v[10:11], v[8:9] op_sel:[1,0,0] op_sel_hi:[0,1,1]
	v_pk_fma_f32 v[8:9], v[138:139], v[12:13], v[8:9] op_sel:[1,0,0] op_sel_hi:[0,1,1]
	v_pk_fma_f32 v[8:9], v[140:141], v[14:15], v[8:9] op_sel:[1,0,0] op_sel_hi:[0,1,1]
	v_add_f32_e32 v8, v9, v8
	v_max_f32_e32 v189, v189, v0
	v_min_f32_e32 v188, v188, v0
	ds_write2st64_b32 v196, v0, v8 offset1:64
	v_max_f32_e32 v16, 0, v16
	v_max_f32_e32 v17, 0, v17
	v_max_f32_e32 v18, 0, v18
	v_max_f32_e32 v19, 0, v19
	v_max_f32_e32 v20, 0, v20
	v_max_f32_e32 v21, 0, v21
	v_max_f32_e32 v22, 0, v22
	v_max_f32_e32 v23, 0, v23
	v_max_f32_e32 v187, v187, v8
	v_min_f32_e32 v186, v186, v8
	s_waitcnt lgkmcnt(0)
	ds_write_b128 v222, v[60:63]
	ds_write_b128 v222, v[48:51] offset:1024
	v_pk_mul_f32 v[16:17], v[142:143], v[16:17] op_sel:[1,0] op_sel_hi:[0,1]
	v_pk_fma_f32 v[16:17], v[144:145], v[18:19], v[16:17] op_sel:[1,0,0] op_sel_hi:[0,1,1]
	v_pk_fma_f32 v[16:17], v[146:147], v[20:21], v[16:17] op_sel:[1,0,0] op_sel_hi:[0,1,1]
	v_pk_fma_f32 v[16:17], v[148:149], v[22:23], v[16:17] op_sel:[1,0,0] op_sel_hi:[0,1,1]
	v_add_f32_e32 v16, v17, v16
	v_max_f32_e32 v24, 0, v24
	v_max_f32_e32 v25, 0, v25
	v_max_f32_e32 v26, 0, v26
	v_max_f32_e32 v27, 0, v27
	v_max_f32_e32 v28, 0, v28
	v_max_f32_e32 v29, 0, v29
	v_max_f32_e32 v30, 0, v30
	v_max_f32_e32 v31, 0, v31
	v_add_u32_e32 v3, 0x10000, v196
	s_waitcnt lgkmcnt(0)
	ds_read_b128 v[100:103], v223
	ds_read_b128 v[96:99], v224
	v_pk_mul_f32 v[24:25], v[150:151], v[24:25] op_sel:[1,0] op_sel_hi:[0,1]
	v_pk_fma_f32 v[24:25], v[152:153], v[26:27], v[24:25] op_sel:[1,0,0] op_sel_hi:[0,1,1]
	v_pk_fma_f32 v[24:25], v[154:155], v[28:29], v[24:25] op_sel:[1,0,0] op_sel_hi:[0,1,1]
	v_pk_fma_f32 v[24:25], v[156:157], v[30:31], v[24:25] op_sel:[1,0,0] op_sel_hi:[0,1,1]
	v_add_f32_e32 v24, v25, v24
	ds_write_b32 v3, v16
	v_max_f32_e32 v185, v185, v16
	v_min_f32_e32 v184, v184, v16
	v_add_u32_e32 v3, 0x14000, v196
	v_add_u32_e32 v196, 0x400, v196
	s_nop 0
	ds_write_b32 v3, v24
	v_max_f32_e32 v183, v183, v24
	v_min_f32_e32 v123, v123, v24
	s_mov_b32 s6, s3

; #define LAS __attribute__((address_space(3)))
; __device__ __forceinline__ void indexer_phase(const bf16_t* PJ, float* rk, unsigned short* SEL, LAS unsigned char* lds) {
;     ...
;                 const int key = 32 * kt + r32;
; #pragma unroll
;                 for (int rt = 0; rt < 2; ++rt) {
;                     f32x16 acc = f32x16{};
; #pragma unroll
;                     for (int kk = 0; kk < 4; ++kk) acc = __builtin_amdgcn_mfma_f32_32x32x16_bf16(af[rt][kk], bcur[kk], acc, 0, 0, 0);
; #pragma unroll
;                     for (int qq = 0; qq < 2; ++qq) { float s = 0.f;
; #pragma unroll
;                         for (int e = 0; e < 8; ++e) s += wq[rt][qq][e] * fmaxf(acc[8 * qq + e], 0.f);
;                         ((LAS float*)lds)[(4 * rt + 2 * hi + qq) * 4096 + key] = s;
;                         const bool ok = key <= t0 + 4 * rt + 2 * hi + qq;
;                         rmax[rt][qq] = fmaxf(rmax[rt][qq], ok ? s : -INFINITY); rmin[rt][qq] = fminf(rmin[rt][qq], ok ? s : INFINITY); }
.Lidx_trB:
	ds_write_b128 v222, v[228:231]
	ds_write_b128 v222, v[232:235] offset:1024
	s_nop 3
	v_max_f32_e32 v0, 0, v0
	v_max_f32_e32 v1, 0, v1
	v_max_f32_e32 v2, 0, v2
	v_max_f32_e32 v3, 0, v3
	v_max_f32_e32 v4, 0, v4
	v_max_f32_e32 v5, 0, v5
	v_max_f32_e32 v6, 0, v6
	v_max_f32_e32 v7, 0, v7
	v_pk_mul_f32 v[0:1], v[126:127], v[0:1] op_sel:[1,0] op_sel_hi:[0,1]
	v_pk_fma_f32 v[0:1], v[128:129], v[2:3], v[0:1] op_sel:[1,0,0] op_sel_hi:[0,1,1]
	v_pk_fma_f32 v[0:1], v[130:131], v[4:5], v[0:1] op_sel:[1,0,0] op_sel_hi:[0,1,1]
	v_pk_fma_f32 v[0:1], v[132:133], v[6:7], v[0:1] op_sel:[1,0,0] op_sel_hi:[0,1,1]
	v_add_f32_e32 v0, v1, v0
	v_max_f32_e32 v8, 0, v8
	v_max_f32_e32 v9, 0, v9
	v_max_f32_e32 v10, 0, v10
	v_max_f32_e32 v11, 0, v11
	v_max_f32_e32 v12, 0, v12
	v_max_f32_e32 v13, 0, v13
	v_max_f32_e32 v14, 0, v14
	v_max_f32_e32 v15, 0, v15
	s_waitcnt lgkmcnt(0)
	ds_read_b128 v[244:247], v223
	ds_read_b128 v[104:107], v224
	v_pk_mul_f32 v[8:9], v[134:135], v[8:9] op_sel:[1,0] op_sel_hi:[0,1]
	v_pk_fma_f32 v[8:9], v[136:137], v[10:11], v[8:9] op_sel:[1,0,0] op_sel_hi:[0,1,1]
	v_pk_fma_f32 v[8:9], v[138:139], v[12:13], v[8:9] op_sel:[1,0,0] op_sel_hi:[0,1,1]
	v_pk_fma_f32 v[8:9], v[140:141], v[14:15], v[8:9] op_sel:[1,0,0] op_sel_hi:[0,1,1]
	v_add_f32_e32 v8, v9, v8
	v_max_f32_e32 v189, v189, v0
	v_min_f32_e32 v188, v188, v0
	ds_write2st64_b32 v196, v0, v8 offset1:64
	v_max_f32_e32 v16, 0, v16
	v_max_f32_e32 v17, 0, v17
	v_max_f32_e32 v18, 0, v18
	v_max_f32_e32 v19, 0, v19
	v_max_f32_e32 v20, 0, v20
	v_max_f32_e32 v21, 0, v21
	v_max_f32_e32 v22, 0, v22
	v_max_f32_e32 v23, 0, v23
	v_max_f32_e32 v187, v187, v8
	v_min_f32_e32 v186, v186, v8
	s_waitcnt lgkmcnt(0)
	ds_write_b128 v222, v[236:239]
	ds_write_b128 v222, v[240:243] offset:1024
	v_pk_mul_f32 v[16:17], v[142:143], v[16:17] op_sel:[1,0] op_sel_hi:[0,1]
	v_pk_fma_f32 v[16:17], v[144:145], v[18:19], v[16:17] op_sel:[1,0,0] op_sel_hi:[0,1,1]
	v_pk_fma_f32 v[16:17], v[146:147], v[20:21], v[16:17] op_sel:[1,0,0] op_sel_hi:[0,1,1]
	v_pk_fma_f32 v[16:17], v[148:149], v[22:23], v[16:17] op_sel:[1,0,0] op_sel_hi:[0,1,1]
	v_add_f32_e32 v16, v17, v16
	v_max_f32_e32 v24, 0, v24
	v_max_f32_e32 v25, 0, v25
	v_max_f32_e32 v26, 0, v26
	v_max_f32_e32 v27, 0, v27
	v_max_f32_e32 v28, 0, v28
	v_max_f32_e32 v29, 0, v29
	v_max_f32_e32 v30, 0, v30
	v_max_f32_e32 v31, 0, v31
	v_add_u32_e32 v3, 0x10000, v196
	s_waitcnt lgkmcnt(0)
	ds_read_b128 v[100:103], v223
	ds_read_b128 v[96:99], v224
	v_pk_mul_f32 v[24:25], v[150:151], v[24:25] op_sel:[1,0] op_sel_hi:[0,1]
	v_pk_fma_f32 v[24:25], v[152:153], v[26:27], v[24:25] op_sel:[1,0,0] op_sel_hi:[0,1,1]
	v_pk_fma_f32 v[24:25], v[154:155], v[28:29], v[24:25] op_sel:[1,0,0] op_sel_hi:[0,1,1]
	v_pk_fma_f32 v[24:25], v[156:157], v[30:31], v[24:25] op_sel:[1,0,0] op_sel_hi:[0,1,1]
	v_add_f32_e32 v24, v25, v24
	ds_write_b32 v3, v16
	v_max_f32_e32 v185, v185, v16
	v_min_f32_e32 v184, v184, v16
	v_add_u32_e32 v3, 0x14000, v196
	v_add_u32_e32 v196, 0x400, v196
	s_nop 0
	ds_write_b32 v3, v24
	v_max_f32_e32 v183, v183, v24
	v_min_f32_e32 v123, v123, v24
	s_mov_b32 s6, s3
	s_branch .Lidx_loopA
.Lidx_last:
	s_waitcnt lgkmcnt(0)
	v_mfma_f32_32x32x16_bf16 v[0:15], v[72:75], v[244:247], 0
	v_add_u32_e32 v197, s6, v110
	v_mfma_f32_32x32x16_bf16 v[0:15], v[64:67], v[104:107], v[0:15]
	v_mfma_f32_32x32x16_bf16 v[0:15], v[68:71], v[100:103], v[0:15]
	v_mfma_f32_32x32x16_bf16 v[0:15], v[76:79], v[96:99], v[0:15]
	v_mfma_f32_32x32x16_bf16 v[16:31], v[88:91], v[244:247], 0
	v_mfma_f32_32x32x16_bf16 v[16:31], v[80:83], v[104:107], v[16:31]
	v_mfma_f32_32x32x16_bf16 v[16:31], v[84:87], v[100:103], v[16:31]
	v_mfma_f32_32x32x16_bf16 v[16:31], v[92:95], v[96:99], v[16:31]
	s_nop 7
	v_max_f32_e32 v0, 0, v0
	v_max_f32_e32 v1, 0, v1
	v_max_f32_e32 v2, 0, v2
	v_max_f32_e32 v3, 0, v3
	v_max_f32_e32 v4, 0, v4
	v_max_f32_e32 v5, 0, v5
	v_max_f32_e32 v6, 0, v6
	v_max_f32_e32 v7, 0, v7
	v_pk_mul_f32 v[0:1], v[126:127], v[0:1] op_sel:[1,0] op_sel_hi:[0,1]
	v_pk_fma_f32 v[0:1], v[128:129], v[2:3], v[0:1] op_sel:[1,0,0] op_sel_hi:[0,1,1]
	v_pk_fma_f32 v[0:1], v[130:131], v[4:5], v[0:1] op_sel:[1,0,0] op_sel_hi:[0,1,1]
	v_pk_fma_f32 v[0:1], v[132:133], v[6:7], v[0:1] op_sel:[1,0,0] op_sel_hi:[0,1,1]
	v_add_f32_e32 v0, v1, v0
	v_max_f32_e32 v8, 0, v8
	v_max_f32_e32 v9, 0, v9
	v_max_f32_e32 v10, 0, v10
	v_max_f32_e32 v11, 0, v11
	v_max_f32_e32 v12, 0, v12
	v_max_f32_e32 v13, 0, v13
	v_max_f32_e32 v14, 0, v14
	v_max_f32_e32 v15, 0, v15
	v_pk_mul_f32 v[8:9], v[134:135], v[8:9] op_sel:[1,0] op_sel_hi:[0,1]
	v_pk_fma_f32 v[8:9], v[136:137], v[10:11], v[8:9] op_sel:[1,0,0] op_sel_hi:[0,1,1]
	v_pk_fma_f32 v[8:9], v[138:139], v[12:13], v[8:9] op_sel:[1,0,0] op_sel_hi:[0,1,1]
	v_pk_fma_f32 v[8:9], v[140:141], v[14:15], v[8:9] op_sel:[1,0,0] op_sel_hi:[0,1,1]
	v_cmp_gt_i32_e32 vcc, v197, v190
	s_nop 1
	v_cndmask_b32_e32 v1, v0, v178, vcc
	v_cndmask_b32_e32 v2, v0, v179, vcc
	v_max_f32_e32 v189, v189, v1
	v_min_f32_e32 v188, v188, v2
	v_add_f32_e32 v8, v9, v8
	v_cmp_gt_i32_e32 vcc, v197, v191
	ds_write2st64_b32 v196, v0, v8 offset1:64
	v_max_f32_e32 v16, 0, v16
	v_max_f32_e32 v17, 0, v17
	v_max_f32_e32 v18, 0, v18
	v_cndmask_b32_e32 v1, v8, v178, vcc
	v_cndmask_b32_e32 v2, v8, v179, vcc
	v_max_f32_e32 v187, v187, v1
	v_min_f32_e32 v186, v186, v2
	v_max_f32_e32 v19, 0, v19
	v_max_f32_e32 v20, 0, v20
	v_max_f32_e32 v21, 0, v21
	v_max_f32_e32 v22, 0, v22
	v_max_f32_e32 v23, 0, v23
	v_pk_mul_f32 v[16:17], v[142:143], v[16:17] op_sel:[1,0] op_sel_hi:[0,1]
	v_pk_fma_f32 v[16:17], v[144:145], v[18:19], v[16:17] op_sel:[1,0,0] op_sel_hi:[0,1,1]
	v_pk_fma_f32 v[16:17], v[146:147], v[20:21], v[16:17] op_sel:[1,0,0] op_sel_hi:[0,1,1]
	v_pk_fma_f32 v[16:17], v[148:149], v[22:23], v[16:17] op_sel:[1,0,0] op_sel_hi:[0,1,1]
	v_add_f32_e32 v16, v17, v16
	v_max_f32_e32 v24, 0, v24
	v_max_f32_e32 v25, 0, v25
	v_max_f32_e32 v26, 0, v26
	v_max_f32_e32 v27, 0, v27
	v_max_f32_e32 v28, 0, v28
	v_max_f32_e32 v29, 0, v29
	v_max_f32_e32 v30, 0, v30
	v_max_f32_e32 v31, 0, v31
	v_pk_mul_f32 v[24:25], v[150:151], v[24:25] op_sel:[1,0] op_sel_hi:[0,1]
	v_pk_fma_f32 v[24:25], v[152:153], v[26:27], v[24:25] op_sel:[1,0,0] op_sel_hi:[0,1,1]
	v_pk_fma_f32 v[24:25], v[154:155], v[28:29], v[24:25] op_sel:[1,0,0] op_sel_hi:[0,1,1]
	v_pk_fma_f32 v[24:25], v[156:157], v[30:31], v[24:25] op_sel:[1,0,0] op_sel_hi:[0,1,1]
	v_cmp_gt_i32_e32 vcc, v197, v192
	v_add_u32_e32 v3, 0x10000, v196
	s_nop 1
	ds_write_b32 v3, v16
	v_cndmask_b32_e32 v1, v16, v178, vcc
	v_cndmask_b32_e32 v2, v16, v179, vcc
	v_max_f32_e32 v185, v185, v1
	v_min_f32_e32 v184, v184, v2
	v_add_f32_e32 v24, v25, v24
	v_cmp_gt_i32_e32 vcc, v197, v193
	v_add_u32_e32 v3, 0x14000, v196
	v_add_u32_e32 v196, 0x400, v196
	s_nop 0
	ds_write_b32 v3, v24
	v_cndmask_b32_e32 v1, v24, v178, vcc
	v_cndmask_b32_e32 v2, v24, v179, vcc
	v_max_f32_e32 v183, v183, v1
	v_min_f32_e32 v123, v123, v2
	s_branch .LBB0_874
